# speedup vs baseline: 1.0013x; 1.0013x over previous
; template <int NT, int BM, int BN, bool PLAIN, int NSTAGE, bool EPI_LDS>
; __device__ __forceinline__ void gemm_tile(const Params& p, const GemmDesc& g, bf16_t* lds, const int tid) {
;     ...
;   const int r0 = tid >> 3, c0 = tid & 7;
;   unsigned aoff[PLAIN ? 1 : NA];
;   const char* abase = (const char*)g.A;
;   if (PLAIN) {
;     abase = (const char*)(g.A + (long)m0 * g.lda_lo);
;     aoff[0] = (unsigned)((r0 * (int)g.lda_lo + c0 * 8) * 2);
;   } else {
; #pragma unroll
;     for (int i = 0; i < NA; ++i) {
;       int ra = m0 + r0 + RP * i;
;       int rlo = ra & g.rmask; rlo = rlo < g.rclamp ? rlo : g.rclamp;
;       aoff[i] = (unsigned)(((long)rlo * g.lda_lo + (long)(ra >> g.rshift) * g.lda_hi + c0 * 8) * 2);
;     }
;   }
;   const char* bbase = (const char*)(g.Bt + (long)n0 * g.ldb);
;   const unsigned boff = (unsigned)((r0 * (int)g.ldb + c0 * 8) * 2);
;   const long astepP = (long)RP * g.lda_lo * 2, bstepP = (long)RP * g.ldb * 2;
;   u32x4 ra4[NA], rb4[NB];
;   f32x4 acc[MI][NI];
; #pragma unroll
;   for (int i = 0; i < MI; ++i)
; #pragma unroll
;     for (int j = 0; j < NI; ++j) acc[i][j] = f32x4{0.f, 0.f, 0.f, 0.f};
;   const int nk = g.K >> 6;
;     ...
;   constexpr int STAGE_BYTES = (BM + BN) * 128;
;   char* const ldsb = (char*)lds;
;   const unsigned woff = (unsigned)(((r0 >> 4) * 2 + (c0 >> 2)) * 1024 + (((((r0 & 15) ^ (c0 >> 2)) * 64) + (c0 & 3) * 16) ^ (((r0 & 15) >> 3) << 5)));
;   const unsigned roff = (unsigned)(((fr * 64) + fq * 16) ^ ((fr >> 3) << 5));
;   const int roff1d = (int)((((fr ^ 1) * 64 + fq * 16) ^ ((fr >> 3) << 5))) - (int)roff;
;     ...
;     GLOAD(0)
;     __syncthreads();
;     LWRITE(0)
;     if (nk > 1) GLOAD(1)
;     __syncthreads();
.LBB0_896:
	v_lshrrev_b32_e32 v0, 6, v224
	v_and_b32_e32 v2, 63, v224
	v_readfirstlane_b32 s57, v0
	v_lshrrev_b32_e32 v3, 3, v2
	v_bfe_u32 v4, v2, 4, 2
	v_and_b32_e32 v5, 3, v2
	v_xor_b32_e32 v4, v4, v5
	v_lshlrev_b32_e32 v4, 4, v4
	v_bfe_u32 v5, v2, 2, 1
	v_lshl_or_b32 v4, v5, 6, v4
	v_xor_b32_e32 v5, 64, v4
	s_cmp_ge_u32 s57, 4
	s_cselect_b32 s58, s26, s52
	s_cselect_b32 s59, s41, s42
	s_cselect_b32 s60, s28, s30
	s_cselect_b32 s61, s29, s31
	s_and_b32 s62, s57, 3
	s_lshl_b32 s62, s62, 6
	s_add_i32 s59, s59, s62
	s_mul_i32 s59, s59, s58
	s_lshl_b32 s58, s58, 1
	s_lshl_b32 s59, s59, 1
	s_add_u32 s60, s60, s59
	s_addc_u32 s61, s61, 0
	v_mul_lo_u32 v3, v3, s58
	s_lshl_b32 s62, s58, 3
	v_add_u32_e32 v162, v3, v4
	v_add3_u32 v163, v3, v5, s62
	s_lshl_b32 s62, s58, 4
	v_add_u32_e32 v164, s62, v162
	v_add_u32_e32 v165, s62, v163
	v_add_u32_e32 v166, s62, v164
	v_add_u32_e32 v167, s62, v165
	v_add_u32_e32 v168, s62, v166
	v_add_u32_e32 v169, s62, v167
	s_lshl_b32 s57, s57, 13
	s_barrier
	s_mov_b32 m0, s57
	v_mov_b32_e32 v110, 0
	v_mov_b32_e32 v111, v110
	v_mov_b32_e32 v112, v110
	v_mov_b32_e32 v113, v110
	v_mov_b32_e32 v90, v110
	v_mov_b32_e32 v91, v110
	v_mov_b32_e32 v92, v110
	v_mov_b32_e32 v93, v110
	v_mov_b32_e32 v40, v110
	v_mov_b32_e32 v41, v110
	global_load_lds_dwordx4 v162, s[60:61]
	s_add_u32 m0, m0, 0x400
	v_mov_b32_e32 v42, v110
	v_mov_b32_e32 v43, v110
	v_mov_b32_e32 v44, v110
	v_mov_b32_e32 v45, v110
	v_mov_b32_e32 v46, v110
	v_mov_b32_e32 v47, v110
	v_mov_b32_e32 v48, v110
	v_mov_b32_e32 v49, v110
	v_mov_b32_e32 v50, v110
	v_mov_b32_e32 v51, v110
	global_load_lds_dwordx4 v163, s[60:61]
	s_add_u32 m0, m0, 0x400
	v_mov_b32_e32 v52, v110
	v_mov_b32_e32 v53, v110
	v_mov_b32_e32 v54, v110
	v_mov_b32_e32 v55, v110
	v_mov_b32_e32 v56, v110
	v_mov_b32_e32 v57, v110
	v_mov_b32_e32 v58, v110
	v_mov_b32_e32 v59, v110
	v_mov_b32_e32 v60, v110
	v_mov_b32_e32 v61, v110
	global_load_lds_dwordx4 v164, s[60:61]
	s_add_u32 m0, m0, 0x400
	v_mov_b32_e32 v62, v110
	v_mov_b32_e32 v63, v110
	v_mov_b32_e32 v64, v110
	v_mov_b32_e32 v65, v110
	v_mov_b32_e32 v66, v110
	v_mov_b32_e32 v67, v110
	v_mov_b32_e32 v68, v110
	v_mov_b32_e32 v69, v110
	v_mov_b32_e32 v70, v110
	v_mov_b32_e32 v71, v110
	global_load_lds_dwordx4 v165, s[60:61]
	s_add_u32 m0, m0, 0x400
	v_mov_b32_e32 v72, v110
	v_mov_b32_e32 v73, v110
	v_mov_b32_e32 v74, v110
	v_mov_b32_e32 v75, v110
	v_mov_b32_e32 v76, v110
	v_mov_b32_e32 v34, v110
	v_mov_b32_e32 v35, v110
	v_mov_b32_e32 v36, v110
	v_mov_b32_e32 v37, v110
	v_mov_b32_e32 v38, v110
	global_load_lds_dwordx4 v166, s[60:61]
	s_add_u32 m0, m0, 0x400
	v_mov_b32_e32 v39, v110
	v_mov_b32_e32 v77, v110
	v_mov_b32_e32 v78, v110
	v_mov_b32_e32 v79, v110
	v_mov_b32_e32 v80, v110
	v_mov_b32_e32 v81, v110
	v_mov_b32_e32 v82, v110
	v_mov_b32_e32 v83, v110
	v_mov_b32_e32 v84, v110
	v_mov_b32_e32 v85, v110
	global_load_lds_dwordx4 v167, s[60:61]
	s_add_u32 m0, m0, 0x400
	v_mov_b32_e32 v86, v110
	v_mov_b32_e32 v87, v110
	v_mov_b32_e32 v88, v110
	v_mov_b32_e32 v89, v110
	v_mov_b32_e32 v94, v110
	v_mov_b32_e32 v95, v110
	v_mov_b32_e32 v96, v110
	v_mov_b32_e32 v97, v110
	v_mov_b32_e32 v98, v110
	v_mov_b32_e32 v99, v110
	global_load_lds_dwordx4 v168, s[60:61]
	s_add_u32 m0, m0, 0x400
	v_mov_b32_e32 v100, v110
	v_mov_b32_e32 v101, v110
	v_mov_b32_e32 v102, v110
	v_mov_b32_e32 v103, v110
	v_mov_b32_e32 v104, v110
	v_mov_b32_e32 v105, v110
	v_mov_b32_e32 v106, v110
	v_mov_b32_e32 v107, v110
	v_mov_b32_e32 v108, v110
	v_mov_b32_e32 v109, v110
	global_load_lds_dwordx4 v169, s[60:61]
	s_add_u32 s60, s60, 0x80
	s_addc_u32 s61, s61, 0
	s_add_u32 m0, s57, 0x10000
	v_mov_b32_e32 v114, v110
	v_mov_b32_e32 v115, v110
	v_mov_b32_e32 v116, v110
	v_mov_b32_e32 v117, v110
	v_mov_b32_e32 v118, v110
	v_mov_b32_e32 v119, v110
	v_mov_b32_e32 v120, v110
	v_mov_b32_e32 v121, v110
	v_mov_b32_e32 v122, v110
	v_mov_b32_e32 v123, v110
	global_load_lds_dwordx4 v162, s[60:61]
	s_add_u32 m0, m0, 0x400
	v_mov_b32_e32 v124, v110
	v_mov_b32_e32 v125, v110
	v_mov_b32_e32 v126, v110
	v_mov_b32_e32 v127, v110
	v_mov_b32_e32 v128, v110
	v_mov_b32_e32 v129, v110
	v_mov_b32_e32 v130, v110
	v_mov_b32_e32 v131, v110
	v_mov_b32_e32 v132, v110
	v_mov_b32_e32 v133, v110
	global_load_lds_dwordx4 v163, s[60:61]
	s_add_u32 m0, m0, 0x400
	v_mov_b32_e32 v134, v110
	v_mov_b32_e32 v135, v110
	v_mov_b32_e32 v136, v110
	v_mov_b32_e32 v137, v110
	v_mov_b32_e32 v138, v110
	v_mov_b32_e32 v139, v110
	v_mov_b32_e32 v140, v110
	v_mov_b32_e32 v141, v110
	v_mov_b32_e32 v142, v110
	v_mov_b32_e32 v143, v110
	global_load_lds_dwordx4 v164, s[60:61]
	s_add_u32 m0, m0, 0x400
	v_mov_b32_e32 v144, v110
	v_mov_b32_e32 v145, v110
	v_mov_b32_e32 v146, v110
	v_mov_b32_e32 v147, v110
	v_mov_b32_e32 v148, v110
	v_mov_b32_e32 v149, v110
	v_mov_b32_e32 v150, v110
	v_mov_b32_e32 v151, v110
	v_mov_b32_e32 v152, v110
	v_mov_b32_e32 v153, v110
	global_load_lds_dwordx4 v165, s[60:61]
	v_mov_b32_e32 v154, v110
	v_mov_b32_e32 v155, v110
	v_mov_b32_e32 v156, v110
	v_mov_b32_e32 v157, v110
	v_mov_b32_e32 v158, v110
	v_mov_b32_e32 v159, v110
	v_mov_b32_e32 v160, v110
	v_mov_b32_e32 v161, v110
	s_add_i32 s3, s23, -2
	s_mov_b32 s26, 0
	s_mov_b32 s27, s3
	s_waitcnt vmcnt(4)
	s_barrier
	v_add_u32_e32 v19, v180, v184
	v_add_u32_e32 v18, v180, v183
	ds_read_b128 v[2:5], v19 offset:32768
	ds_read_b128 v[6:9], v19 offset:34816
	ds_read_b128 v[10:13], v19 offset:36864
	ds_read_b128 v[14:17], v19 offset:38912
	ds_read_b128 v[202:205], v18
	ds_read_b128 v[206:209], v18 offset:2048
	ds_read_b128 v[226:229], v18 offset:4096
